# move w2 weight transposes from in-proj tail into mixer-phase idle time on non-scan workgroups
# speedup vs baseline: 1.0025x; 1.0025x over previous
; __device__ __forceinline__ void phase_wconv_rest(const Params& p, LAS unsigned char* lds, int gw, int NGW) {
;     ...
;     for (int it = gw; it < NITEMS; it += NGW) {
;         int r = it;
;         if (r < I_A) { transpose_item<false, false>(p.w_a, WA, D_MODEL, (bf16*)(ws + WS_WAT), 0, scr, r, lane); continue; } r -= I_A;
;         if (r < I_A) { transpose_item<false, false>(p.w_b, WA, D_MODEL, (bf16*)(ws + WS_WBT), 0, scr, r, lane); continue; } r -= I_A;
;         if (r < I_O) { transpose_item<false, false>(p.w_o, D_MODEL, D_MODEL, (bf16*)(ws + WS_WOT), 0, scr, r, lane); continue; } r -= I_O;
;         if (r < I_1) { transpose_item<false, true>(p.w1, D_MODEL, FFN, (bf16*)(ws + WS_W13T), 0, scr, r, lane, sh2, b2); continue; } r -= I_1;
;         if (r < I_1) { transpose_item<false, true>(p.w3, D_MODEL, FFN, (bf16*)(ws + WS_W13T), 128, scr, r, lane, sh2, b2); continue; } r -= I_1;
;         transpose_item<false, false>(p.w2, FFN, D_MODEL, (bf16*)(ws + WS_W2T), 0, scr, r, lane);
; __global__ void __launch_bounds__(NTHREADS, 2) mega_fwd(Params p_in) {
;     ...
;       const int nfree = nb - CTX_UNITS;
;       if (nfree >= 64) { if (bx >= CTX_UNITS) phase_wconv_rest(p, lds, (bx - CTX_UNITS) * 8 + wave_id, nfree * 8); }
.LBB0_240:
	s_cmpk_lt_i32 s2, 0x50
	s_cbranch_scc1 .LBB0_268
	s_lshl_b32 s4, s2, 3
	s_add_i32 s4, s4, s3
	s_add_i32 s20, s4, 0xfffffd80
	s_cmpk_gt_i32 s20, 0x3bff
	v_mbcnt_lo_u32_b32 v0, -1, 0
	v_mbcnt_hi_u32_b32 v0, -1, v0
	s_cbranch_scc1 .LBB0_268
	s_add_i32 s21, s46, 0xfffffd80
	s_waitcnt lgkmcnt(0)
	s_add_u32 s6, s22, 0x106000
	s_addc_u32 s7, s23, 0
	s_add_u32 s16, s22, 0x18000
	s_addc_u32 s17, s23, 0
	s_lshl_b32 s3, s3, 14
	v_ashrrev_i32_e32 v34, 5, v0
	v_lshlrev_b32_e32 v1, 2, v0
	s_movk_i32 s4, 0x84
	s_add_i32 s3, s3, 0
	v_and_b32_e32 v22, 0x7c, v1
	v_mul_lo_u32 v1, v34, s4
	v_add3_u32 v26, s3, v22, v1
	v_lshlrev_b32_e32 v1, 3, v0
	v_and_b32_e32 v1, 56, v1
	v_ashrrev_i32_e32 v35, 3, v0
	v_lshlrev_b32_e32 v12, 1, v1
	v_mov_b32_e32 v13, 0
	v_mul_u32_u24_e32 v4, 0x84, v1
	v_lshl_add_u64 v[10:11], s[22:23], 0, v[12:13]
	v_lshlrev_b32_e32 v1, 2, v35
	s_mov_b64 s[22:23], 0x142000
	v_add3_u32 v27, s3, v4, v1
	v_lshl_add_u64 v[4:5], v[10:11], 0, s[22:23]
	s_mov_b64 s[22:23], 0x4b42000
	v_lshl_add_u64 v[6:7], v[10:11], 0, s[22:23]
	s_mov_b64 s[22:23], 0x4742000
	s_mov_b64 s[4:5], 0x2d42000
	v_ashrrev_i32_e32 v1, 31, v0
	v_lshl_add_u64 v[8:9], v[10:11], 0, s[22:23]
	s_mov_b64 s[22:23], 0x4342000
	v_mov_b32_e32 v23, v13
	s_mov_b32 s19, 0
	v_lshl_add_u64 v[2:3], v[10:11], 0, s[4:5]
	v_add_u32_e32 v36, 8, v35
	v_add_u32_e32 v37, 16, v35
	v_add_u32_e32 v38, 24, v35
	v_cmp_gt_i32_e64 s[4:5], 32, v0
	v_lshl_add_u64 v[10:11], v[10:11], 0, s[22:23]
	v_lshl_add_u64 v[12:13], s[42:43], 0, v[22:23]
	v_lshl_add_u64 v[14:15], s[40:41], 0, v[22:23]
	v_lshl_add_u64 v[16:17], s[14:15], 0, v[22:23]
	v_lshl_add_u64 v[18:19], s[12:13], 0, v[22:23]
	v_lshl_add_u64 v[20:21], s[10:11], 0, v[22:23]
	v_lshl_add_u64 v[22:23], s[8:9], 0, v[22:23]
	v_lshl_add_u64 v[24:25], v[0:1], 2, s[16:17]
	s_lshl_b32 s3, s20, 5
	s_lshl_b32 s12, s21, 5
	s_mov_b32 s13, 0xc000
	s_mov_b32 s14, 0x18000
	s_mov_b32 s15, 0x24000
	s_movk_i32 s22, 0x2c00
	s_movk_i32 s23, 0x5800
	v_add_u32_e32 v39, 0x4000, v26
	v_add_u32_e32 v40, 0x4400, v26
	v_add_u32_e32 v41, 0x4800, v26
	v_add_u32_e32 v42, 0x4c00, v26
	v_add_u32_e32 v43, 0x5000, v26
	v_add_u32_e32 v44, 0x5400, v26
	v_add_u32_e32 v45, 0x5800, v26
	v_add_u32_e32 v46, 0x5c00, v26
	v_add_u32_e32 v47, 0x4000, v27
	s_branch .LBB0_244
.LBB0_243:
	s_add_i32 s20, s20, s21
	s_add_i32 s3, s3, s12
	s_cmpk_gt_i32 s20, 0x3bff
	s_cbranch_scc1 .LBB0_268

; __device__ __forceinline__ int lane_id() { int l; asm volatile("v_mbcnt_lo_u32_b32 %0, -1, 0\n\tv_mbcnt_hi_u32_b32 %0, -1, %0" : "=v"(l)); return l; }
; #define LOAD_P() Params p; { const __attribute__((address_space(4))) Params* q_ = (const __attribute__((address_space(4))) Params*)__builtin_amdgcn_kernarg_segment_ptr(); asm volatile("" : "+s"(q_)); \
;     p = *q_; p.wave_id = wave_id; } unsigned char* ws = p.ws; (void)ws
; __device__ __forceinline__ void phase_wconv_rest(const Params& p, LAS unsigned char* lds, int gw, int NGW) {
;     ...
;     for (int it = gw; it < NITEMS; it += NGW) {
;         int r = it;
;         if (r < I_A) { transpose_item<false, false>(p.w_a, WA, D_MODEL, (bf16*)(ws + WS_WAT), 0, scr, r, lane); continue; } r -= I_A;
;         if (r < I_A) { transpose_item<false, false>(p.w_b, WA, D_MODEL, (bf16*)(ws + WS_WBT), 0, scr, r, lane); continue; } r -= I_A;
;         if (r < I_O) { transpose_item<false, false>(p.w_o, D_MODEL, D_MODEL, (bf16*)(ws + WS_WOT), 0, scr, r, lane); continue; } r -= I_O;
;         if (r < I_1) { transpose_item<false, true>(p.w1, D_MODEL, FFN, (bf16*)(ws + WS_W13T), 0, scr, r, lane, sh2, b2); continue; } r -= I_1;
;         if (r < I_1) { transpose_item<false, true>(p.w3, D_MODEL, FFN, (bf16*)(ws + WS_W13T), 128, scr, r, lane, sh2, b2); continue; } r -= I_1;
;         transpose_item<false, false>(p.w2, FFN, D_MODEL, (bf16*)(ws + WS_W2T), 0, scr, r, lane);
; __global__ void __launch_bounds__(NTHREADS, 2) mega_fwd(Params p_in) {
;     ...
;     { LOAD_P();
;       if (bx < 2 * BATCH * NHEAD) {
;         if (wave_id == 0 && lane_id() == 0) { unsigned* pc = (unsigned*)(ws + WS_PREPCTR); while (__hip_atomic_load(pc, __ATOMIC_RELAXED, __HIP_MEMORY_SCOPE_AGENT) < (unsigned)nb) __builtin_amdgcn_s_sleep(2); }
;         asm volatile("" ::: "memory"); __syncthreads();
;         hgrn_scan(p, lds, bx); }
;       __syncthreads();
;       phase_attn(p, lds); }
.LBB0_505:
	s_cmpk_lt_i32 s2, 0x40
	s_cbranch_scc1 .Lw2_skip
	v_writelane_b32 v250, s3, 40
	v_writelane_b32 v250, s12, 41
	v_writelane_b32 v250, s18, 42
	v_writelane_b32 v250, s19, 43
	v_writelane_b32 v250, s20, 44
	v_writelane_b32 v250, s21, 45
	v_writelane_b32 v250, s22, 46
	v_writelane_b32 v250, s23, 47
	v_writelane_b32 v250, s24, 48
	v_writelane_b32 v250, s25, 49
	v_writelane_b32 v250, s26, 50
	v_writelane_b32 v250, s27, 51
	s_lshr_b32 s3, s76, 6
	s_load_dwordx8 s[8:15], s[0:1], 0x70
	s_load_dwordx2 s[40:41], s[0:1], 0x90
	s_load_dwordx2 s[42:43], s[0:1], 0xa8
	s_load_dwordx2 s[22:23], s[0:1], 0xb8
	s_waitcnt vmcnt(0) lgkmcnt(0)
	s_barrier
	s_lshl_b32 s4, s2, 3
	s_add_i32 s4, s4, s3
	s_add_i32 s20, s4, 0x3a00
	s_cmpk_gt_i32 s20, 0x51ff
	v_mbcnt_lo_u32_b32 v0, -1, 0
	v_mbcnt_hi_u32_b32 v0, -1, v0
	s_cbranch_scc1 .Lw2_done
	s_movk_i32 s21, 0x600
	s_waitcnt lgkmcnt(0)
	s_add_u32 s6, s22, 0x106000
	s_addc_u32 s7, s23, 0
	s_add_u32 s16, s22, 0x18000
	s_addc_u32 s17, s23, 0
	s_lshl_b32 s3, s3, 14
	v_ashrrev_i32_e32 v34, 5, v0
	v_lshlrev_b32_e32 v1, 2, v0
	s_movk_i32 s4, 0x84
	s_add_i32 s3, s3, 0
	v_and_b32_e32 v22, 0x7c, v1
	v_mul_lo_u32 v1, v34, s4
	v_add3_u32 v26, s3, v22, v1
	v_lshlrev_b32_e32 v1, 3, v0
	v_and_b32_e32 v1, 56, v1
	v_ashrrev_i32_e32 v35, 3, v0
	v_lshlrev_b32_e32 v12, 1, v1
	v_mov_b32_e32 v13, 0
	v_mul_u32_u24_e32 v4, 0x84, v1
	v_lshl_add_u64 v[10:11], s[22:23], 0, v[12:13]
	v_lshlrev_b32_e32 v1, 2, v35
	s_mov_b64 s[22:23], 0x142000
	v_add3_u32 v27, s3, v4, v1
	v_lshl_add_u64 v[4:5], v[10:11], 0, s[22:23]
	s_mov_b64 s[22:23], 0x4b42000
	v_lshl_add_u64 v[6:7], v[10:11], 0, s[22:23]
	s_mov_b64 s[22:23], 0x4742000
	s_mov_b64 s[4:5], 0x2d42000
	v_ashrrev_i32_e32 v1, 31, v0
	v_lshl_add_u64 v[8:9], v[10:11], 0, s[22:23]
	s_mov_b64 s[22:23], 0x4342000
	v_mov_b32_e32 v23, v13
	s_mov_b32 s19, 0
	v_lshl_add_u64 v[2:3], v[10:11], 0, s[4:5]
	v_add_u32_e32 v36, 8, v35
	v_add_u32_e32 v37, 16, v35
	v_add_u32_e32 v38, 24, v35
	v_cmp_gt_i32_e64 s[4:5], 32, v0
	v_lshl_add_u64 v[10:11], v[10:11], 0, s[22:23]
	v_lshl_add_u64 v[12:13], s[42:43], 0, v[22:23]
	v_lshl_add_u64 v[14:15], s[40:41], 0, v[22:23]
	v_lshl_add_u64 v[16:17], s[14:15], 0, v[22:23]
	v_lshl_add_u64 v[18:19], s[12:13], 0, v[22:23]
	v_lshl_add_u64 v[20:21], s[10:11], 0, v[22:23]
	v_lshl_add_u64 v[22:23], s[8:9], 0, v[22:23]
	v_lshl_add_u64 v[24:25], v[0:1], 2, s[16:17]
	s_lshl_b32 s3, s20, 5
	s_lshl_b32 s12, s21, 5
	s_mov_b32 s13, 0xc000
	s_mov_b32 s14, 0x18000
	s_mov_b32 s15, 0x24000
	s_movk_i32 s22, 0x2c00
	s_movk_i32 s23, 0x5800
	v_add_u32_e32 v39, 0x4000, v26
	v_add_u32_e32 v40, 0x4400, v26
	v_add_u32_e32 v41, 0x4800, v26
	v_add_u32_e32 v42, 0x4c00, v26
	v_add_u32_e32 v43, 0x5000, v26
	v_add_u32_e32 v44, 0x5400, v26
	v_add_u32_e32 v45, 0x5800, v26
	v_add_u32_e32 v46, 0x5c00, v26
	v_add_u32_e32 v47, 0x4000, v27
	s_branch .Lw2c_244

; __device__ __forceinline__ int lane_id() { int l; asm volatile("v_mbcnt_lo_u32_b32 %0, -1, 0\n\tv_mbcnt_hi_u32_b32 %0, -1, %0" : "=v"(l)); return l; }
; #define LOAD_P() Params p; { const __attribute__((address_space(4))) Params* q_ = (const __attribute__((address_space(4))) Params*)__builtin_amdgcn_kernarg_segment_ptr(); asm volatile("" : "+s"(q_)); \
;     p = *q_; p.wave_id = wave_id; } unsigned char* ws = p.ws; (void)ws
; __global__ void __launch_bounds__(NTHREADS, 2) mega_fwd(Params p_in) {
;     ...
;     { LOAD_P();
;       if (bx < 2 * BATCH * NHEAD) {
;         if (wave_id == 0 && lane_id() == 0) { unsigned* pc = (unsigned*)(ws + WS_PREPCTR); while (__hip_atomic_load(pc, __ATOMIC_RELAXED, __HIP_MEMORY_SCOPE_AGENT) < (unsigned)nb) __builtin_amdgcn_s_sleep(2); }
;         asm volatile("" ::: "memory"); __syncthreads();
;         hgrn_scan(p, lds, bx); }
;       __syncthreads();
;       phase_attn(p, lds); }
.Lw2_done:
	v_readlane_b32 s3, v250, 40
	v_readlane_b32 s12, v250, 41
	v_readlane_b32 s18, v250, 42
	v_readlane_b32 s19, v250, 43
	v_readlane_b32 s20, v250, 44
	v_readlane_b32 s21, v250, 45
	v_readlane_b32 s22, v250, 46
	v_readlane_b32 s23, v250, 47
	v_readlane_b32 s24, v250, 48
	v_readlane_b32 s25, v250, 49
	v_readlane_b32 s26, v250, 50
	v_readlane_b32 s27, v250, 51
	s_nop 4
